# E37: attention K/V tile prefetch issued at start of each P1 into dedicated staging VGPRs (v194-199,v220-223,v244-253) instead of mid-P1
# baseline (speedup 1.0000x reference)
.LBB0_2191:
	s_add_u32 s6, s50, 0x8000
	s_addc_u32 s7, s51, 0
	v_lshl_add_u64 v[194:195], s[6:7], 0, v[144:145]
	s_add_u32 s6, s50, 0xa000
	s_addc_u32 s7, s51, 0
	v_lshl_add_u64 v[220:221], s[6:7], 0, v[144:145]
	s_add_u32 s6, s50, s64
	s_addc_u32 s7, s51, 0
	v_lshl_add_u64 v[244:245], s[6:7], 0, v[142:143]
	global_load_dwordx4 v[194:197], v[194:195], off
	global_load_dwordx4 v[220:223], v[220:221], off
	global_load_dwordx4 v[248:251], v[244:245], off offset:128
	global_load_dwordx2 v[198:199], v[244:245], off offset:256
	global_load_dwordx2 v[252:253], v[244:245], off offset:264
	global_load_dwordx4 v[244:247], v[244:245], off
	ds_read_b128 v[64:67], v156 offset:57344
	ds_read_b128 v[200:203], v169 offset:57344
	v_add_u32_e32 v191, v190, v155
	ds_read_b128 v[68:71], v191 offset:12288
	v_add_u32_e32 v193, v190, v175
	ds_read_b128 v[204:207], v193 offset:12288
	v_add_u32_e32 v192, v190, v176
	v_add_f32_e32 v132, 0, v133
	v_add_f32_e32 v132, v214, v132
	s_waitcnt lgkmcnt(3)
	v_mfma_f32_32x32x16_bf16 v[80:95], v[64:67], v[108:111], 0
	v_add_f32_e32 v132, v134, v132
	v_add_f32_e32 v132, v215, v132
	v_add_f32_e32 v132, v213, v132
	v_add_f32_e32 v132, v216, v132
	v_add_f32_e32 v132, v135, v132
	v_add_f32_e32 v132, v212, v132
	v_add_f32_e32 v132, v146, v132
	s_waitcnt lgkmcnt(2)
	v_mfma_f32_32x32x16_bf16 v[80:95], v[200:203], v[104:107], v[80:95]
	ds_read_b128 v[200:203], v168 offset:57344
	v_add_f32_e32 v132, v148, v132
	v_add_f32_e32 v132, v147, v132
	v_add_f32_e32 v132, v149, v132
	v_exp_f32_e32 v126, v126
	v_add_f32_e32 v132, v128, v132
	v_exp_f32_e32 v127, v127
	s_waitcnt lgkmcnt(2)
	v_mfma_f32_32x32x16_bf16 v[64:79], v[68:71], v[108:111], 0
	v_add_f32_e32 v132, v130, v132
	v_exp_f32_e32 v124, v124
	v_add_f32_e32 v132, v129, v132
	v_exp_f32_e32 v125, v125
	v_add_f32_e32 v132, v131, v132
	v_exp_f32_e32 v120, v120
	v_add_f32_e32 v132, v126, v132
	s_waitcnt lgkmcnt(1)
	v_mfma_f32_32x32x16_bf16 v[64:79], v[204:207], v[104:107], v[64:79]
	ds_read_b128 v[204:207], v192 offset:12288
	v_exp_f32_e32 v121, v121
	v_add_f32_e32 v132, v127, v132
	v_exp_f32_e32 v116, v116
	v_add_f32_e32 v132, v124, v132
	v_exp_f32_e32 v117, v117
	v_add_f32_e32 v132, v125, v132
	s_waitcnt lgkmcnt(1)
	v_mfma_f32_32x32x16_bf16 v[80:95], v[200:203], v[100:103], v[80:95]
	v_add_u32_e32 v200, v190, v177
	v_add_u32_e32 v201, v190, v178
	v_exp_f32_e32 v114, v114
	v_add_f32_e32 v132, v120, v132
	v_exp_f32_e32 v115, v115
	v_add_f32_e32 v132, v121, v132
	v_exp_f32_e32 v122, v122
	s_waitcnt lgkmcnt(0)
	v_mfma_f32_32x32x16_bf16 v[64:79], v[204:207], v[100:103], v[64:79]
	ds_read_b128 v[202:205], v167 offset:57344
	ds_read_b128 v[206:209], v200 offset:12288
	v_add_f32_e32 v132, v116, v132
	v_exp_f32_e32 v123, v123
	v_add_f32_e32 v132, v117, v132
	v_exp_f32_e32 v118, v118
	v_add_f32_e32 v132, v114, v132
	s_waitcnt lgkmcnt(1)
	v_mfma_f32_32x32x16_bf16 v[80:95], v[202:205], v[96:99], v[80:95]
	ds_read_b128 v[202:205], v165 offset:57344
	v_exp_f32_e32 v119, v119
	v_add_f32_e32 v132, v115, v132
	v_exp_f32_e32 v112, v112
	v_add_f32_e32 v132, v122, v132
	v_exp_f32_e32 v113, v113
	v_add_f32_e32 v132, v123, v132
	s_waitcnt lgkmcnt(1)
	v_mfma_f32_32x32x16_bf16 v[64:79], v[206:209], v[96:99], v[64:79]
	ds_read_b128 v[206:209], v201 offset:12288
	ds_read_b128 v[224:227], v139
	v_add_f32_e32 v132, v118, v132
	v_add_f32_e32 v132, v119, v132
	v_add_f32_e32 v132, v112, v132
	s_waitcnt lgkmcnt(0)
	v_mfma_f32_32x32x16_bf16 v[64:79], v[206:209], v[224:227], v[64:79]
	ds_read_b128 v[206:209], v166 offset:57344
	v_mfma_f32_32x32x16_bf16 v[80:95], v[202:205], v[224:227], v[80:95]
	v_add_u32_e32 v204, v190, v181
	ds_read_b128 v[224:227], v204 offset:12288
	ds_read_b128 v[228:231], v139 offset:1024
	v_add_u32_e32 v202, v190, v182
	v_add_u32_e32 v203, v190, v183
	v_add_u32_e32 v205, v190, v185
	s_waitcnt lgkmcnt(0)
	v_mfma_f32_32x32x16_bf16 v[80:95], v[206:209], v[228:231], v[80:95]
	ds_read_b128 v[206:209], v158 offset:57344
	v_mfma_f32_32x32x16_bf16 v[64:79], v[224:227], v[228:231], v[64:79]
	ds_read_b128 v[224:227], v202 offset:12288
	ds_read_b128 v[228:231], v139 offset:2048
	s_waitcnt lgkmcnt(0)
	v_mfma_f32_32x32x16_bf16 v[80:95], v[206:209], v[228:231], v[80:95]
	ds_read_b128 v[206:209], v157 offset:57344
	v_mfma_f32_32x32x16_bf16 v[64:79], v[224:227], v[228:231], v[64:79]
	ds_read_b128 v[224:227], v203 offset:12288
	ds_read_b128 v[228:231], v139 offset:3072
	s_waitcnt lgkmcnt(0)
	v_mfma_f32_32x32x16_bf16 v[80:95], v[206:209], v[228:231], v[80:95]
	ds_read_b128 v[208:211], v154 offset:57344
	v_add_u32_e32 v206, v190, v184
	v_add_u32_e32 v207, v190, v186
	v_mfma_f32_32x32x16_bf16 v[64:79], v[224:227], v[228:231], v[64:79]
	ds_read_b128 v[224:227], v206 offset:12288
	ds_read_b128 v[228:231], v139 offset:4096
	s_waitcnt lgkmcnt(0)
	v_mfma_f32_32x32x16_bf16 v[80:95], v[208:211], v[228:231], v[80:95]
	ds_read_b128 v[208:211], v153 offset:57344
	v_mfma_f32_32x32x16_bf16 v[64:79], v[224:227], v[228:231], v[64:79]
	ds_read_b128 v[224:227], v205 offset:12288
	ds_read_b128 v[228:231], v139 offset:5120
	s_waitcnt lgkmcnt(0)
	v_mfma_f32_32x32x16_bf16 v[80:95], v[208:211], v[228:231], v[80:95]
	ds_read_b128 v[208:211], v180 offset:57344
	v_mfma_f32_32x32x16_bf16 v[64:79], v[224:227], v[228:231], v[64:79]
	ds_read_b128 v[224:227], v207 offset:12288
	ds_read_b128 v[228:231], v139 offset:6144
	s_waitcnt lgkmcnt(0)
	v_mfma_f32_32x32x16_bf16 v[64:79], v[224:227], v[228:231], v[64:79]
	ds_read_b128 v[224:227], v179 offset:57344
	v_mfma_f32_32x32x16_bf16 v[80:95], v[208:211], v[228:231], v[80:95]
	v_add_u32_e32 v208, v190, v187
	ds_read_b128 v[228:231], v208 offset:12288
	ds_read_b128 v[232:235], v139 offset:7168
	v_add_f32_e32 v209, v113, v132
	v_mov_b32_e32 v210, v209
	v_cvt_pk_bf16_f32 v132, v133, v214
	v_cvt_pk_bf16_f32 v133, v134, v215
	v_cvt_pk_bf16_f32 v134, v213, v216
	s_waitcnt lgkmcnt(0)
	v_mfma_f32_32x32x16_bf16 v[80:95], v[224:227], v[232:235], v[80:95]
	v_permlane32_swap_b32_e32 v209, v210
	v_cvt_pk_bf16_f32 v135, v135, v212
	v_permlane32_swap_b32_e32 v132, v134
	v_cvt_pk_bf16_f32 v212, v146, v148
	v_cvt_pk_bf16_f32 v213, v147, v149
	v_mfma_f32_32x32x16_bf16 v[64:79], v[228:231], v[232:235], v[64:79]
	v_cvt_pk_bf16_f32 v214, v128, v130
	v_cvt_pk_bf16_f32 v215, v129, v131
	v_cvt_pk_bf16_f32 v216, v126, v127
	v_cvt_pk_bf16_f32 v217, v124, v125
	v_cvt_pk_bf16_f32 v218, v120, v121
	v_cvt_pk_bf16_f32 v219, v116, v117
	v_cvt_pk_bf16_f32 v224, v114, v115
	v_cvt_pk_bf16_f32 v225, v122, v123
	v_cvt_pk_bf16_f32 v226, v118, v119
	v_cvt_pk_bf16_f32 v227, v112, v113
	v_permlane32_swap_b32_e32 v133, v135
	v_permlane32_swap_b32_e32 v212, v214
	v_permlane32_swap_b32_e32 v213, v215
	v_permlane32_swap_b32_e32 v216, v218
	v_permlane32_swap_b32_e32 v217, v219
	v_permlane32_swap_b32_e32 v224, v226
	v_permlane32_swap_b32_e32 v225, v227
	ds_read_b64_tr_b16 v[228:229], v152 offset:0
	ds_read_b64_tr_b16 v[230:231], v152 offset:0x800
	ds_read_b64_tr_b16 v[232:233], v152 offset:0x1000
	ds_read_b64_tr_b16 v[234:235], v152 offset:0x1800
	ds_read_b64_tr_b16 v[236:237], v152 offset:0x2000
	ds_read_b64_tr_b16 v[238:239], v152 offset:0x2800
	ds_read_b64_tr_b16 v[240:241], v152 offset:0x3000
	ds_read_b64_tr_b16 v[242:243], v152 offset:0x3800
	s_waitcnt lgkmcnt(0)
	s_nop 0
	v_mfma_f32_32x32x16_bf16 v[0:15], v[132:135], v[228:231], v[0:15]
	ds_read_b64_tr_b16 v[228:229], v152 offset:0x200
	ds_read_b64_tr_b16 v[230:231], v152 offset:0xa00
	v_mfma_f32_32x32x16_bf16 v[0:15], v[212:215], v[232:235], v[0:15]
	ds_read_b64_tr_b16 v[232:233], v152 offset:0x1200
	ds_read_b64_tr_b16 v[234:235], v152 offset:0x1a00
	v_mfma_f32_32x32x16_bf16 v[0:15], v[216:219], v[236:239], v[0:15]
	ds_read_b64_tr_b16 v[236:237], v152 offset:0x2200
	ds_read_b64_tr_b16 v[238:239], v152 offset:0x2a00
	v_mfma_f32_32x32x16_bf16 v[0:15], v[224:227], v[240:243], v[0:15]
	ds_read_b64_tr_b16 v[240:241], v152 offset:0x3200
	ds_read_b64_tr_b16 v[242:243], v152 offset:0x3a00
	s_waitcnt lgkmcnt(0)
	v_mfma_f32_32x32x16_bf16 v[48:63], v[132:135], v[228:231], v[48:63]
	ds_read_b64_tr_b16 v[228:229], v152 offset:0x400
	ds_read_b64_tr_b16 v[230:231], v152 offset:0xc00
	v_mfma_f32_32x32x16_bf16 v[48:63], v[212:215], v[232:235], v[48:63]
	ds_read_b64_tr_b16 v[232:233], v152 offset:0x1400
	ds_read_b64_tr_b16 v[234:235], v152 offset:0x1c00
	v_mfma_f32_32x32x16_bf16 v[48:63], v[216:219], v[236:239], v[48:63]
	ds_read_b64_tr_b16 v[236:237], v152 offset:0x2400
	ds_read_b64_tr_b16 v[238:239], v152 offset:0x2c00
	v_mfma_f32_32x32x16_bf16 v[48:63], v[224:227], v[240:243], v[48:63]
	ds_read_b64_tr_b16 v[240:241], v152 offset:0x3400
	ds_read_b64_tr_b16 v[242:243], v152 offset:0x3c00
	s_waitcnt lgkmcnt(0)
	v_mfma_f32_32x32x16_bf16 v[32:47], v[132:135], v[228:231], v[32:47]
	ds_read_b64_tr_b16 v[228:229], v152 offset:0x600
	ds_read_b64_tr_b16 v[230:231], v152 offset:0xe00
	v_mfma_f32_32x32x16_bf16 v[32:47], v[212:215], v[232:235], v[32:47]
	ds_read_b64_tr_b16 v[232:233], v152 offset:0x1600
	ds_read_b64_tr_b16 v[234:235], v152 offset:0x1e00
	v_mfma_f32_32x32x16_bf16 v[32:47], v[216:219], v[236:239], v[32:47]
	ds_read_b64_tr_b16 v[236:237], v152 offset:0x2600
	ds_read_b64_tr_b16 v[238:239], v152 offset:0x2e00
	v_mfma_f32_32x32x16_bf16 v[32:47], v[224:227], v[240:243], v[32:47]
	ds_read_b64_tr_b16 v[240:241], v152 offset:0x3600
	ds_read_b64_tr_b16 v[242:243], v152 offset:0x3e00
	s_waitcnt lgkmcnt(0)
	v_mfma_f32_32x32x16_bf16 v[16:31], v[132:135], v[228:231], v[16:31]
	v_max_f32_e32 v132, v81, v81
	v_max_f32_e32 v133, v80, v80
	v_max_f32_e32 v132, v133, v132
	v_max3_f32 v132, v132, v82, v83
	v_max3_f32 v132, v132, v84, v85
	v_max3_f32 v132, v132, v86, v87
	v_max3_f32 v132, v132, v88, v89
	v_max3_f32 v132, v132, v90, v91
	v_max3_f32 v132, v132, v92, v93
	v_mfma_f32_32x32x16_bf16 v[16:31], v[212:215], v[232:235], v[16:31]
	v_max3_f32 v132, v132, v94, v95
	v_max3_f32 v132, v132, v64, v65
	v_max3_f32 v132, v132, v66, v67
	v_max3_f32 v132, v132, v68, v69
	v_max3_f32 v132, v132, v70, v71
	v_max3_f32 v132, v132, v72, v73
	v_max3_f32 v132, v132, v74, v75
	v_max3_f32 v132, v132, v76, v77
	v_mfma_f32_32x32x16_bf16 v[16:31], v[216:219], v[236:239], v[16:31]
	v_max3_f32 v132, v132, v78, v79
	v_mov_b32_e32 v133, v132
	s_nop 1
	v_permlane32_swap_b32_e32 v132, v133
	v_max_f32_e32 v133, v133, v133
	v_max_f32_e32 v132, v132, v132
	v_max_f32_e32 v132, v132, v133
	v_sub_f32_e32 v133, v132, v188
	v_cmp_ge_f32_e32 vcc, s1, v133
	v_max_f32_e32 v133, v188, v188
	v_max_f32_e32 v132, v133, v132
	v_mfma_f32_32x32x16_bf16 v[16:31], v[224:227], v[240:243], v[16:31]
	v_sub_f32_e32 v133, v188, v132
	v_mul_f32_e32 v133, 0x3dd53b94, v133
	v_exp_f32_e32 v133, v133
	s_cmp_eq_u64 vcc, exec
	s_cselect_b64 s[6:7], -1, 0
	s_barrier
	s_waitcnt vmcnt(0)
	v_cndmask_b32_e64 v211, v133, 1.0, s[6:7]
	v_cmp_gt_f32_e32 vcc, 1.0, v211
	ds_write_b128 v163, v[194:197]
	ds_write_b128 v164, v[220:223]
	ds_write_b128 v159, v[244:247] offset:32768
	ds_write_b128 v159, v[248:251] offset:32896
	ds_write_b64 v159, v[198:199] offset:33024
	ds_write_b64 v159, v[252:253] offset:33032
	s_cbranch_vccz .LBB0_2195
	s_and_saveexec_b64 s[10:11], s[4:5]
	ds_write_b32 v174, v211 offset:128
	s_or_b64 exec, exec, s[10:11]
	s_waitcnt lgkmcnt(0)
	v_add_u32_e32 v124, v137, v160
	ds_read_b128 v[112:115], v124 offset:224
	ds_read_b128 v[116:119], v124 offset:192
	ds_read_b128 v[120:123], v124 offset:160
	ds_read_b128 v[124:127], v124 offset:128
	s_waitcnt lgkmcnt(3)
	v_pk_mul_f32 v[12:13], v[12:13], v[112:113]
	s_waitcnt lgkmcnt(2)
	v_pk_mul_f32 v[8:9], v[8:9], v[116:117]
	s_waitcnt lgkmcnt(1)
	v_pk_mul_f32 v[4:5], v[4:5], v[120:121]
	v_pk_mul_f32 v[14:15], v[14:15], v[114:115]
	v_pk_mul_f32 v[10:11], v[10:11], v[118:119]
	v_pk_mul_f32 v[6:7], v[6:7], v[122:123]
	s_waitcnt lgkmcnt(0)
	v_pk_mul_f32 v[2:3], v[2:3], v[126:127]
	v_pk_mul_f32 v[0:1], v[0:1], v[124:125]
	v_pk_mul_f32 v[60:61], v[60:61], v[112:113]
	v_pk_mul_f32 v[56:57], v[56:57], v[116:117]
	v_pk_mul_f32 v[52:53], v[52:53], v[120:121]
	v_pk_mul_f32 v[62:63], v[62:63], v[114:115]
	v_pk_mul_f32 v[58:59], v[58:59], v[118:119]
	v_pk_mul_f32 v[54:55], v[54:55], v[122:123]
	v_pk_mul_f32 v[50:51], v[50:51], v[126:127]
	v_pk_mul_f32 v[48:49], v[48:49], v[124:125]
	v_pk_mul_f32 v[44:45], v[44:45], v[112:113]
	v_pk_mul_f32 v[40:41], v[40:41], v[116:117]
	v_pk_mul_f32 v[36:37], v[36:37], v[120:121]
	v_pk_mul_f32 v[46:47], v[46:47], v[114:115]
	v_pk_mul_f32 v[42:43], v[42:43], v[118:119]
	v_pk_mul_f32 v[38:39], v[38:39], v[122:123]
	v_pk_mul_f32 v[34:35], v[34:35], v[126:127]
	v_pk_mul_f32 v[32:33], v[32:33], v[124:125]
	v_pk_mul_f32 v[28:29], v[28:29], v[112:113]
	v_pk_mul_f32 v[24:25], v[24:25], v[116:117]
	v_pk_mul_f32 v[20:21], v[20:21], v[120:121]
	v_pk_mul_f32 v[30:31], v[30:31], v[114:115]
	v_pk_mul_f32 v[26:27], v[26:27], v[118:119]
	v_pk_mul_f32 v[22:23], v[22:23], v[122:123]
	v_pk_mul_f32 v[18:19], v[18:19], v[126:127]
	v_pk_mul_f32 v[16:17], v[16:17], v[124:125]
.LBB0_2195:
	v_cndmask_b32_e64 v188, v132, v188, s[6:7]
	v_mul_f32_e32 v128, 0xbdd53b94, v188
	v_fmamk_f32 v80, v80, 0x3dd53b94, v128
	v_fmamk_f32 v81, v81, 0x3dd53b94, v128
	v_fmamk_f32 v82, v82, 0x3dd53b94, v128
	v_fmamk_f32 v83, v83, 0x3dd53b94, v128
	v_fmamk_f32 v84, v84, 0x3dd53b94, v128
	v_fmamk_f32 v85, v85, 0x3dd53b94, v128
	v_fmamk_f32 v86, v86, 0x3dd53b94, v128
	v_fmamk_f32 v87, v87, 0x3dd53b94, v128
	v_fmamk_f32 v88, v88, 0x3dd53b94, v128
	v_fmamk_f32 v89, v89, 0x3dd53b94, v128
	v_fmamk_f32 v90, v90, 0x3dd53b94, v128
	v_fmamk_f32 v91, v91, 0x3dd53b94, v128
	v_fmamk_f32 v92, v92, 0x3dd53b94, v128
	v_fmamk_f32 v93, v93, 0x3dd53b94, v128
	v_fmamk_f32 v94, v94, 0x3dd53b94, v128
	v_fmamk_f32 v95, v95, 0x3dd53b94, v128
	v_fmamk_f32 v217, v68, 0x3dd53b94, v128
	v_fmamk_f32 v132, v71, 0x3dd53b94, v128
	v_fmamk_f32 v133, v72, 0x3dd53b94, v128
	v_fmamk_f32 v218, v77, 0x3dd53b94, v128
	v_fmamk_f32 v213, v64, 0x3dd53b94, v128
	v_fmamk_f32 v214, v65, 0x3dd53b94, v128
	v_fmamk_f32 v215, v66, 0x3dd53b94, v128
	v_fmamk_f32 v216, v67, 0x3dd53b94, v128
	v_fmamk_f32 v130, v69, 0x3dd53b94, v128
	v_fmamk_f32 v131, v70, 0x3dd53b94, v128
	v_fmamk_f32 v134, v73, 0x3dd53b94, v128
	v_fmamk_f32 v135, v74, 0x3dd53b94, v128
	v_fmamk_f32 v212, v75, 0x3dd53b94, v128
	v_fmamk_f32 v129, v76, 0x3dd53b94, v128
	v_exp_f32_e32 v125, v80
	v_exp_f32_e32 v127, v81
	v_exp_f32_e32 v123, v82
	v_exp_f32_e32 v126, v83
	v_exp_f32_e32 v122, v84
	v_exp_f32_e32 v124, v85
	v_exp_f32_e32 v120, v86
	v_exp_f32_e32 v121, v87
	v_exp_f32_e32 v117, v88
	v_exp_f32_e32 v119, v89
	v_exp_f32_e32 v116, v90
	v_exp_f32_e32 v118, v91
	v_exp_f32_e32 v113, v92
	v_exp_f32_e32 v115, v93
	v_exp_f32_e32 v112, v94
	v_exp_f32_e32 v114, v95
	v_fmamk_f32 v219, v78, 0x3dd53b94, v128
	v_fmac_f32_e32 v128, 0x3dd53b94, v79
	s_waitcnt lgkmcnt(0)
	s_barrier
	s_add_u32 s6, s50, s64
	s_addc_u32 s7, s51, 0
	v_lshl_add_u64 v[194:195], s[6:7], 0, v[144:145]
	s_add_u32 s6, s50, 0xe000
	s_addc_u32 s7, s51, 0
	v_lshl_add_u64 v[220:221], s[6:7], 0, v[144:145]
	s_add_u32 s6, s50, 0x12000
	s_addc_u32 s7, s51, 0
	v_lshl_add_u64 v[244:245], s[6:7], 0, v[142:143]
	global_load_dwordx4 v[194:197], v[194:195], off
	global_load_dwordx4 v[220:223], v[220:221], off
	global_load_dwordx4 v[248:251], v[244:245], off offset:128
	global_load_dwordx2 v[198:199], v[244:245], off offset:256
	global_load_dwordx2 v[252:253], v[244:245], off offset:264
	global_load_dwordx4 v[244:247], v[244:245], off
	ds_read_b128 v[64:67], v156 offset:32768
	ds_read_b128 v[68:71], v156 offset:45056
	ds_read_b128 v[224:227], v169 offset:32768
	ds_read_b128 v[228:231], v169 offset:45056
	v_exp_f32_e32 v216, v216
	v_exp_f32_e32 v130, v130
	s_waitcnt lgkmcnt(3)
	v_mfma_f32_32x32x16_bf16 v[80:95], v[64:67], v[108:111], 0
	v_exp_f32_e32 v131, v131
	v_exp_f32_e32 v129, v129
	v_exp_f32_e32 v219, v219
	v_exp_f32_e32 v128, v128
	s_waitcnt lgkmcnt(2)
	v_mfma_f32_32x32x16_bf16 v[64:79], v[68:71], v[108:111], 0
	s_waitcnt lgkmcnt(0)
	v_mfma_f32_32x32x16_bf16 v[64:79], v[228:231], v[104:107], v[64:79]
	v_mfma_f32_32x32x16_bf16 v[80:95], v[224:227], v[104:107], v[80:95]
	ds_read_b128 v[224:227], v168 offset:32768
	ds_read_b128 v[228:231], v168 offset:45056
	s_waitcnt lgkmcnt(0)
	v_mfma_f32_32x32x16_bf16 v[64:79], v[228:231], v[100:103], v[64:79]
	v_mfma_f32_32x32x16_bf16 v[80:95], v[224:227], v[100:103], v[80:95]
	ds_read_b128 v[224:227], v167 offset:32768
	ds_read_b128 v[228:231], v167 offset:45056
	s_waitcnt lgkmcnt(0)
	v_mfma_f32_32x32x16_bf16 v[64:79], v[228:231], v[96:99], v[64:79]
	v_mfma_f32_32x32x16_bf16 v[80:95], v[224:227], v[96:99], v[80:95]
	ds_read_b128 v[224:227], v165 offset:32768
	ds_read_b128 v[228:231], v165 offset:45056
	ds_read_b128 v[232:235], v139
	s_waitcnt lgkmcnt(0)
	v_mfma_f32_32x32x16_bf16 v[64:79], v[228:231], v[232:235], v[64:79]
	v_mfma_f32_32x32x16_bf16 v[80:95], v[224:227], v[232:235], v[80:95]
	ds_read_b128 v[224:227], v166 offset:32768
	ds_read_b128 v[228:231], v166 offset:45056
	ds_read_b128 v[232:235], v139 offset:1024
	s_waitcnt lgkmcnt(0)
	v_mfma_f32_32x32x16_bf16 v[64:79], v[228:231], v[232:235], v[64:79]
	v_mfma_f32_32x32x16_bf16 v[80:95], v[224:227], v[232:235], v[80:95]
	ds_read_b128 v[224:227], v158 offset:32768
	ds_read_b128 v[228:231], v158 offset:45056
	ds_read_b128 v[232:235], v139 offset:2048
	s_waitcnt lgkmcnt(0)
	v_mfma_f32_32x32x16_bf16 v[64:79], v[228:231], v[232:235], v[64:79]
	v_mfma_f32_32x32x16_bf16 v[80:95], v[224:227], v[232:235], v[80:95]
	ds_read_b128 v[224:227], v157 offset:32768
	ds_read_b128 v[228:231], v157 offset:45056
	ds_read_b128 v[232:235], v139 offset:3072
	s_waitcnt lgkmcnt(0)
	v_mfma_f32_32x32x16_bf16 v[64:79], v[228:231], v[232:235], v[64:79]
	v_mfma_f32_32x32x16_bf16 v[80:95], v[224:227], v[232:235], v[80:95]
	ds_read_b128 v[224:227], v154 offset:32768
	ds_read_b128 v[228:231], v154 offset:45056
	ds_read_b128 v[232:235], v139 offset:4096
	s_waitcnt lgkmcnt(0)
	v_mfma_f32_32x32x16_bf16 v[64:79], v[228:231], v[232:235], v[64:79]
	v_mfma_f32_32x32x16_bf16 v[80:95], v[224:227], v[232:235], v[80:95]
	ds_read_b128 v[224:227], v153 offset:32768
	ds_read_b128 v[228:231], v153 offset:45056
	ds_read_b128 v[232:235], v139 offset:5120
	s_waitcnt lgkmcnt(0)
	v_mfma_f32_32x32x16_bf16 v[64:79], v[228:231], v[232:235], v[64:79]
	v_mfma_f32_32x32x16_bf16 v[80:95], v[224:227], v[232:235], v[80:95]
	ds_read_b128 v[224:227], v180 offset:32768
	ds_read_b128 v[228:231], v180 offset:45056
	ds_read_b128 v[232:235], v139 offset:6144
	s_waitcnt lgkmcnt(0)
	v_mfma_f32_32x32x16_bf16 v[64:79], v[228:231], v[232:235], v[64:79]
	v_mfma_f32_32x32x16_bf16 v[80:95], v[224:227], v[232:235], v[80:95]
	ds_read_b128 v[224:227], v179 offset:32768
	ds_read_b128 v[228:231], v179 offset:45056
	ds_read_b128 v[232:235], v139 offset:7168
	s_waitcnt lgkmcnt(0)
	v_mfma_f32_32x32x16_bf16 v[64:79], v[228:231], v[232:235], v[64:79]
	v_exp_f32_e32 v228, v132
	v_add_f32_e32 v132, 0, v125
	v_add_f32_e32 v132, v127, v132
	v_add_f32_e32 v132, v123, v132
	v_add_f32_e32 v132, v126, v132
	v_add_f32_e32 v132, v122, v132
	v_add_f32_e32 v132, v124, v132
	v_add_f32_e32 v132, v120, v132
	v_add_f32_e32 v132, v121, v132
	v_add_f32_e32 v132, v117, v132
	v_add_f32_e32 v132, v119, v132
	v_add_f32_e32 v132, v116, v132
	v_add_f32_e32 v132, v118, v132
	v_mfma_f32_32x32x16_bf16 v[80:95], v[224:227], v[232:235], v[80:95]
	v_exp_f32_e32 v224, v213
	v_add_f32_e32 v132, v113, v132
	v_exp_f32_e32 v225, v214
	v_add_f32_e32 v132, v115, v132
	v_exp_f32_e32 v226, v215
	v_add_f32_e32 v132, v112, v132
	v_add_f32_e32 v132, v114, v132
	v_exp_f32_e32 v227, v217
	v_add_f32_e32 v132, v224, v132
	v_add_f32_e32 v132, v225, v132
	v_add_f32_e32 v132, v226, v132
	v_add_f32_e32 v132, v216, v132
	v_exp_f32_e32 v229, v133
	v_add_f32_e32 v132, v227, v132
	v_exp_f32_e32 v230, v134
	v_add_f32_e32 v132, v130, v132
	v_exp_f32_e32 v231, v135
	v_add_f32_e32 v132, v131, v132
	v_exp_f32_e32 v232, v212
	v_add_f32_e32 v132, v228, v132
	v_add_f32_e32 v132, v229, v132
	v_exp_f32_e32 v233, v218
	v_add_f32_e32 v132, v230, v132
	v_add_f32_e32 v132, v231, v132
	v_add_f32_e32 v132, v232, v132
	v_add_f32_e32 v132, v129, v132
	v_add_f32_e32 v132, v233, v132
	v_add_f32_e32 v132, v219, v132
	v_add_f32_e32 v217, v128, v132
	v_mov_b32_e32 v218, v217
	v_cvt_pk_bf16_f32 v132, v125, v127
	v_cvt_pk_bf16_f32 v133, v123, v126
	v_cvt_pk_bf16_f32 v134, v122, v124
	v_cvt_pk_bf16_f32 v135, v120, v121
	s_nop 1
	v_permlane32_swap_b32_e32 v217, v218
	v_permlane32_swap_b32_e32 v132, v134
	v_permlane32_swap_b32_e32 v133, v135
	v_cvt_pk_bf16_f32 v212, v117, v119
	v_cvt_pk_bf16_f32 v213, v116, v118
	v_cvt_pk_bf16_f32 v214, v113, v115
	v_cvt_pk_bf16_f32 v215, v112, v114
	v_cvt_pk_bf16_f32 v224, v224, v225
	v_cvt_pk_bf16_f32 v225, v226, v216
	v_cvt_pk_bf16_f32 v226, v227, v130
	v_cvt_pk_bf16_f32 v227, v131, v228
	v_cvt_pk_bf16_f32 v228, v229, v230
	v_cvt_pk_bf16_f32 v229, v231, v232
	v_cvt_pk_bf16_f32 v230, v129, v233
	v_cvt_pk_bf16_f32 v231, v219, v128
	s_nop 0
	v_permlane32_swap_b32_e32 v212, v214
	v_permlane32_swap_b32_e32 v213, v215
	v_permlane32_swap_b32_e32 v224, v226
	v_permlane32_swap_b32_e32 v225, v227
	v_permlane32_swap_b32_e32 v228, v230
	v_permlane32_swap_b32_e32 v229, v231
	ds_read_b64_tr_b16 v[146:147], v150 offset:0
	ds_read_b64_tr_b16 v[148:149], v150 offset:0x800
	ds_read_b64_tr_b16 v[232:233], v150 offset:0x1000
	ds_read_b64_tr_b16 v[234:235], v150 offset:0x1800
	ds_read_b64_tr_b16 v[236:237], v150 offset:0x2000
	ds_read_b64_tr_b16 v[238:239], v150 offset:0x2800
	ds_read_b64_tr_b16 v[240:241], v150 offset:0x3000
	ds_read_b64_tr_b16 v[242:243], v150 offset:0x3800
	s_waitcnt lgkmcnt(0)
	s_nop 0
	v_mfma_f32_32x32x16_bf16 v[0:15], v[132:135], v[146:149], v[0:15]
	ds_read_b64_tr_b16 v[146:147], v150 offset:0x200
	ds_read_b64_tr_b16 v[148:149], v150 offset:0xa00
	v_mfma_f32_32x32x16_bf16 v[0:15], v[212:215], v[232:235], v[0:15]
	ds_read_b64_tr_b16 v[232:233], v150 offset:0x1200
	ds_read_b64_tr_b16 v[234:235], v150 offset:0x1a00
	v_mfma_f32_32x32x16_bf16 v[0:15], v[224:227], v[236:239], v[0:15]
	ds_read_b64_tr_b16 v[236:237], v150 offset:0x2200
	ds_read_b64_tr_b16 v[238:239], v150 offset:0x2a00
	v_mfma_f32_32x32x16_bf16 v[0:15], v[228:231], v[240:243], v[0:15]
	ds_read_b64_tr_b16 v[240:241], v150 offset:0x3200
	ds_read_b64_tr_b16 v[242:243], v150 offset:0x3a00
	s_waitcnt lgkmcnt(0)
	v_mfma_f32_32x32x16_bf16 v[48:63], v[132:135], v[146:149], v[48:63]
	ds_read_b64_tr_b16 v[146:147], v150 offset:0x400
	ds_read_b64_tr_b16 v[148:149], v150 offset:0xc00
	v_mfma_f32_32x32x16_bf16 v[48:63], v[212:215], v[232:235], v[48:63]
	ds_read_b64_tr_b16 v[232:233], v150 offset:0x1400
	ds_read_b64_tr_b16 v[234:235], v150 offset:0x1c00
	v_mfma_f32_32x32x16_bf16 v[48:63], v[224:227], v[236:239], v[48:63]
	ds_read_b64_tr_b16 v[236:237], v150 offset:0x2400
	ds_read_b64_tr_b16 v[238:239], v150 offset:0x2c00
	v_mfma_f32_32x32x16_bf16 v[48:63], v[228:231], v[240:243], v[48:63]
	ds_read_b64_tr_b16 v[240:241], v150 offset:0x3400
	ds_read_b64_tr_b16 v[242:243], v150 offset:0x3c00
	s_waitcnt lgkmcnt(0)
	v_mfma_f32_32x32x16_bf16 v[32:47], v[132:135], v[146:149], v[32:47]
	ds_read_b64_tr_b16 v[146:147], v150 offset:0x600
	ds_read_b64_tr_b16 v[148:149], v150 offset:0xe00
	v_mfma_f32_32x32x16_bf16 v[32:47], v[212:215], v[232:235], v[32:47]
	ds_read_b64_tr_b16 v[232:233], v150 offset:0x1600
	ds_read_b64_tr_b16 v[234:235], v150 offset:0x1e00
	v_mfma_f32_32x32x16_bf16 v[32:47], v[224:227], v[236:239], v[32:47]
	ds_read_b64_tr_b16 v[236:237], v150 offset:0x2600
	ds_read_b64_tr_b16 v[238:239], v150 offset:0x2e00
	v_mfma_f32_32x32x16_bf16 v[32:47], v[228:231], v[240:243], v[32:47]
	ds_read_b64_tr_b16 v[240:241], v150 offset:0x3600
	ds_read_b64_tr_b16 v[242:243], v150 offset:0x3e00
	s_waitcnt lgkmcnt(0)
	v_mfma_f32_32x32x16_bf16 v[16:31], v[132:135], v[146:149], v[16:31]
	v_max_f32_e32 v132, v81, v81
	v_max_f32_e32 v133, v80, v80
	v_max_f32_e32 v132, v133, v132
	v_max3_f32 v132, v132, v82, v83
	v_max3_f32 v132, v132, v84, v85
	v_max3_f32 v132, v132, v86, v87
	v_max3_f32 v132, v132, v88, v89
	v_max3_f32 v132, v132, v90, v91
	v_max3_f32 v132, v132, v92, v93
	v_mfma_f32_32x32x16_bf16 v[16:31], v[212:215], v[232:235], v[16:31]
	v_max3_f32 v132, v132, v94, v95
	v_max3_f32 v132, v132, v64, v65
	v_max3_f32 v132, v132, v66, v67
	v_max3_f32 v132, v132, v68, v69
	v_max3_f32 v132, v132, v70, v71
	v_max3_f32 v132, v132, v72, v73
	v_max3_f32 v132, v132, v74, v75
	v_max3_f32 v132, v132, v76, v77
	v_mfma_f32_32x32x16_bf16 v[16:31], v[224:227], v[236:239], v[16:31]
	v_max3_f32 v132, v132, v78, v79
	v_mov_b32_e32 v133, v132
	s_nop 1
	v_permlane32_swap_b32_e32 v132, v133
	v_max_f32_e32 v133, v133, v133
	v_max_f32_e32 v132, v132, v132
	v_max_f32_e32 v132, v132, v133
	v_sub_f32_e32 v133, v132, v188
	v_cmp_ge_f32_e32 vcc, s1, v133
	v_max_f32_e32 v133, v188, v188
	v_max_f32_e32 v133, v133, v132
	v_mfma_f32_32x32x16_bf16 v[16:31], v[228:231], v[240:243], v[16:31]
	v_sub_f32_e32 v132, v188, v133
	v_mul_f32_e32 v132, 0x3dd53b94, v132
	v_exp_f32_e32 v132, v132
	s_cmp_eq_u64 vcc, exec
	s_cselect_b64 s[6:7], -1, 0
	s_barrier
	s_waitcnt vmcnt(0)
	v_cndmask_b32_e64 v132, v132, 1.0, s[6:7]
	v_cmp_gt_f32_e32 vcc, 1.0, v132
	ds_write_b128 v163, v[194:197] offset:16384
	ds_write_b128 v164, v[220:223] offset:16384
	ds_write_b128 v159, v[244:247] offset:57344
	ds_write_b128 v159, v[248:251] offset:57472
	ds_write_b64 v159, v[198:199] offset:57600
	ds_write_b64 v159, v[252:253] offset:57608
	s_cbranch_vccz .LBB0_2199
	s_and_saveexec_b64 s[10:11], s[4:5]
	ds_write_b32 v174, v132 offset:128
	s_or_b64 exec, exec, s[10:11]
	s_waitcnt lgkmcnt(0)
	v_add_u32_e32 v124, v137, v160
	ds_read_b128 v[112:115], v124 offset:224
	ds_read_b128 v[116:119], v124 offset:192
	ds_read_b128 v[120:123], v124 offset:160
	ds_read_b128 v[124:127], v124 offset:128
	s_waitcnt lgkmcnt(3)
	v_pk_mul_f32 v[12:13], v[12:13], v[112:113]
	s_waitcnt lgkmcnt(2)
	v_pk_mul_f32 v[8:9], v[8:9], v[116:117]
	s_waitcnt lgkmcnt(1)
	v_pk_mul_f32 v[4:5], v[4:5], v[120:121]
	v_pk_mul_f32 v[14:15], v[14:15], v[114:115]
	v_pk_mul_f32 v[10:11], v[10:11], v[118:119]
	v_pk_mul_f32 v[6:7], v[6:7], v[122:123]
	s_waitcnt lgkmcnt(0)
	v_pk_mul_f32 v[2:3], v[2:3], v[126:127]
	v_pk_mul_f32 v[0:1], v[0:1], v[124:125]
	v_pk_mul_f32 v[60:61], v[60:61], v[112:113]
	v_pk_mul_f32 v[56:57], v[56:57], v[116:117]
	v_pk_mul_f32 v[52:53], v[52:53], v[120:121]
	v_pk_mul_f32 v[62:63], v[62:63], v[114:115]
	v_pk_mul_f32 v[58:59], v[58:59], v[118:119]
	v_pk_mul_f32 v[54:55], v[54:55], v[122:123]
	v_pk_mul_f32 v[50:51], v[50:51], v[126:127]
	v_pk_mul_f32 v[48:49], v[48:49], v[124:125]
	v_pk_mul_f32 v[44:45], v[44:45], v[112:113]
	v_pk_mul_f32 v[40:41], v[40:41], v[116:117]
	v_pk_mul_f32 v[36:37], v[36:37], v[120:121]
	v_pk_mul_f32 v[46:47], v[46:47], v[114:115]
	v_pk_mul_f32 v[42:43], v[42:43], v[118:119]
	v_pk_mul_f32 v[38:39], v[38:39], v[122:123]
	v_pk_mul_f32 v[34:35], v[34:35], v[126:127]
	v_pk_mul_f32 v[32:33], v[32:33], v[124:125]
	v_pk_mul_f32 v[28:29], v[28:29], v[112:113]
	v_pk_mul_f32 v[24:25], v[24:25], v[116:117]
	v_pk_mul_f32 v[20:21], v[20:21], v[120:121]
	v_pk_mul_f32 v[30:31], v[30:31], v[114:115]
	v_pk_mul_f32 v[26:27], v[26:27], v[118:119]
	v_pk_mul_f32 v[22:23], v[22:23], v[122:123]
	v_pk_mul_f32 v[18:19], v[18:19], v[126:127]
	v_pk_mul_f32 v[16:17], v[16:17], v[124:125]

.LBB0_2201:
	v_mov_b32_e32 v194, 0x1000
	v_mov_b32_e32 v195, 1
	v_mov_b32_e32 v196, s94
	v_mbcnt_lo_u32_b32 v197, -1, 0
	v_mbcnt_hi_u32_b32 v197, -1, v197
	v_mov_b32_e32 v198, 0xf149f2ca
	v_mov_b32_e32 v220, 0
	v_mov_b32_e32 v221, 0
	v_mov_b32_e32 v222, 0
	v_mov_b32_e32 v223, 0
	v_mov_b32_e32 v199, v197
	ds_read_b128 v[64:67], v156 offset:57344
	ds_read_b128 v[68:71], v191 offset:12288
	v_exp_f32_e32 v116, v116
	v_exp_f32_e32 v117, v117
	v_exp_f32_e32 v114, v114
	s_waitcnt lgkmcnt(1)
	v_mfma_f32_32x32x16_bf16 v[80:95], v[64:67], v[108:111], 0
	v_exp_f32_e32 v115, v115
	v_exp_f32_e32 v118, v118
	v_exp_f32_e32 v119, v119
	v_exp_f32_e32 v113, v113
	s_waitcnt lgkmcnt(0)
	v_mfma_f32_32x32x16_bf16 v[64:79], v[68:71], v[108:111], 0
	ds_read_b128 v[108:111], v169 offset:57344
	ds_read_b128 v[142:145], v193 offset:12288
	s_waitcnt lgkmcnt(1)
	v_mfma_f32_32x32x16_bf16 v[80:95], v[108:111], v[104:107], v[80:95]
	s_waitcnt lgkmcnt(0)
	v_mfma_f32_32x32x16_bf16 v[64:79], v[142:145], v[104:107], v[64:79]
	ds_read_b128 v[104:107], v168 offset:57344
	ds_read_b128 v[108:111], v192 offset:12288
	s_waitcnt lgkmcnt(1)
	v_mfma_f32_32x32x16_bf16 v[80:95], v[104:107], v[100:103], v[80:95]
	s_waitcnt lgkmcnt(0)
	v_mfma_f32_32x32x16_bf16 v[64:79], v[108:111], v[100:103], v[64:79]
	ds_read_b128 v[100:103], v167 offset:57344
	ds_read_b128 v[104:107], v200 offset:12288
	v_exp_f32_e32 v108, v124
	v_exp_f32_e32 v109, v125
	v_exp_f32_e32 v110, v120
	v_exp_f32_e32 v111, v121
	v_exp_f32_e32 v120, v122
	v_exp_f32_e32 v121, v123
	s_waitcnt lgkmcnt(1)
	v_mfma_f32_32x32x16_bf16 v[80:95], v[100:103], v[96:99], v[80:95]
	v_exp_f32_e32 v122, v112
	s_waitcnt lgkmcnt(0)
	v_mfma_f32_32x32x16_bf16 v[64:79], v[104:107], v[96:99], v[64:79]
	ds_read_b128 v[96:99], v165 offset:57344
	ds_read_b128 v[100:103], v201 offset:12288
	ds_read_b128 v[104:107], v139
	s_waitcnt lgkmcnt(0)
	v_mfma_f32_32x32x16_bf16 v[80:95], v[96:99], v[104:107], v[80:95]
	v_mfma_f32_32x32x16_bf16 v[64:79], v[100:103], v[104:107], v[64:79]
	ds_read_b128 v[96:99], v166 offset:57344
	ds_read_b128 v[100:103], v204 offset:12288
	ds_read_b128 v[104:107], v139 offset:1024
	s_waitcnt lgkmcnt(0)
	v_mfma_f32_32x32x16_bf16 v[80:95], v[96:99], v[104:107], v[80:95]
	v_mfma_f32_32x32x16_bf16 v[64:79], v[100:103], v[104:107], v[64:79]
	ds_read_b128 v[96:99], v158 offset:57344
	ds_read_b128 v[100:103], v202 offset:12288
	ds_read_b128 v[104:107], v139 offset:2048
	s_waitcnt lgkmcnt(0)
	v_mfma_f32_32x32x16_bf16 v[80:95], v[96:99], v[104:107], v[80:95]
	v_mfma_f32_32x32x16_bf16 v[64:79], v[100:103], v[104:107], v[64:79]
	ds_read_b128 v[96:99], v157 offset:57344
	ds_read_b128 v[100:103], v203 offset:12288
	ds_read_b128 v[104:107], v139 offset:3072
	s_waitcnt lgkmcnt(0)
	v_mfma_f32_32x32x16_bf16 v[80:95], v[96:99], v[104:107], v[80:95]
	v_mfma_f32_32x32x16_bf16 v[64:79], v[100:103], v[104:107], v[64:79]
	ds_read_b128 v[96:99], v154 offset:57344
	ds_read_b128 v[100:103], v206 offset:12288
	ds_read_b128 v[104:107], v139 offset:4096
	s_waitcnt lgkmcnt(0)
	v_mfma_f32_32x32x16_bf16 v[80:95], v[96:99], v[104:107], v[80:95]
	v_mfma_f32_32x32x16_bf16 v[64:79], v[100:103], v[104:107], v[64:79]
	ds_read_b128 v[96:99], v153 offset:57344
	ds_read_b128 v[100:103], v205 offset:12288
	ds_read_b128 v[104:107], v139 offset:5120
	s_waitcnt lgkmcnt(0)
	v_mfma_f32_32x32x16_bf16 v[80:95], v[96:99], v[104:107], v[80:95]
	v_mfma_f32_32x32x16_bf16 v[64:79], v[100:103], v[104:107], v[64:79]
	ds_read_b128 v[96:99], v180 offset:57344
	ds_read_b128 v[100:103], v207 offset:12288
	ds_read_b128 v[104:107], v139 offset:6144
	s_waitcnt lgkmcnt(0)
	v_mfma_f32_32x32x16_bf16 v[80:95], v[96:99], v[104:107], v[80:95]
	v_mfma_f32_32x32x16_bf16 v[64:79], v[100:103], v[104:107], v[64:79]
	ds_read_b128 v[96:99], v179 offset:57344
	ds_read_b128 v[100:103], v208 offset:12288
	ds_read_b128 v[104:107], v139 offset:7168
	s_waitcnt lgkmcnt(0)
	v_mfma_f32_32x32x16_bf16 v[80:95], v[96:99], v[104:107], v[80:95]
	v_add_f32_e32 v96, 0, v133
	v_add_f32_e32 v96, v214, v96
	v_add_f32_e32 v96, v134, v96
	v_add_f32_e32 v96, v215, v96
	v_add_f32_e32 v96, v213, v96
	v_add_f32_e32 v96, v216, v96
	v_add_f32_e32 v96, v135, v96
	v_add_f32_e32 v96, v212, v96
	v_add_f32_e32 v96, v146, v96
	v_add_f32_e32 v96, v148, v96
	v_add_f32_e32 v96, v147, v96
	v_add_f32_e32 v96, v149, v96
	v_mfma_f32_32x32x16_bf16 v[64:79], v[100:103], v[104:107], v[64:79]
	v_exp_f32_e32 v106, v126
	v_add_f32_e32 v96, v128, v96
	v_exp_f32_e32 v107, v127
	v_add_f32_e32 v96, v130, v96
	v_add_f32_e32 v96, v129, v96
	v_add_f32_e32 v96, v131, v96
	v_add_f32_e32 v96, v106, v96
	v_add_f32_e32 v96, v107, v96
	v_add_f32_e32 v96, v108, v96
	v_add_f32_e32 v96, v109, v96
	v_add_f32_e32 v96, v110, v96
	v_add_f32_e32 v96, v111, v96
	v_add_f32_e32 v96, v116, v96
	v_add_f32_e32 v96, v117, v96
	v_add_f32_e32 v96, v114, v96
	v_add_f32_e32 v96, v115, v96
	v_add_f32_e32 v96, v120, v96
	v_add_f32_e32 v96, v121, v96
	v_add_f32_e32 v96, v118, v96
	v_add_f32_e32 v96, v119, v96
	v_add_f32_e32 v96, v122, v96
	v_add_f32_e32 v96, v113, v96
	v_mov_b32_e32 v97, v96
	v_cvt_pk_bf16_f32 v98, v133, v214
	v_cvt_pk_bf16_f32 v99, v134, v215
	v_cvt_pk_bf16_f32 v100, v213, v216
	v_cvt_pk_bf16_f32 v101, v135, v212
	s_nop 1
	v_permlane32_swap_b32_e32 v96, v97
	v_permlane32_swap_b32_e32 v98, v100
	v_permlane32_swap_b32_e32 v99, v101
	v_cvt_pk_bf16_f32 v102, v146, v148
	v_cvt_pk_bf16_f32 v103, v147, v149
	v_cvt_pk_bf16_f32 v104, v128, v130
	v_cvt_pk_bf16_f32 v105, v129, v131
	v_cvt_pk_bf16_f32 v106, v106, v107
	v_cvt_pk_bf16_f32 v107, v108, v109
	v_cvt_pk_bf16_f32 v108, v110, v111
	v_cvt_pk_bf16_f32 v109, v116, v117
	v_cvt_pk_bf16_f32 v110, v114, v115
	v_cvt_pk_bf16_f32 v111, v120, v121
	v_cvt_pk_bf16_f32 v112, v118, v119
	v_cvt_pk_bf16_f32 v113, v122, v113
	s_nop 0
	v_permlane32_swap_b32_e32 v102, v104
	v_permlane32_swap_b32_e32 v103, v105
	v_permlane32_swap_b32_e32 v106, v108
	v_permlane32_swap_b32_e32 v107, v109
	v_permlane32_swap_b32_e32 v110, v112
	v_permlane32_swap_b32_e32 v111, v113
	ds_read_b64_tr_b16 v[114:115], v152 offset:0
	ds_read_b64_tr_b16 v[116:117], v152 offset:0x800
	ds_read_b64_tr_b16 v[118:119], v152 offset:0x1000
	ds_read_b64_tr_b16 v[120:121], v152 offset:0x1800
	ds_read_b64_tr_b16 v[122:123], v152 offset:0x2000
	ds_read_b64_tr_b16 v[124:125], v152 offset:0x2800
	ds_read_b64_tr_b16 v[126:127], v152 offset:0x3000
	ds_read_b64_tr_b16 v[128:129], v152 offset:0x3800
	s_waitcnt lgkmcnt(0)
	s_nop 0
	v_mfma_f32_32x32x16_bf16 v[0:15], v[98:101], v[114:117], v[0:15]
	ds_read_b64_tr_b16 v[114:115], v152 offset:0x200
	ds_read_b64_tr_b16 v[116:117], v152 offset:0xa00
	v_mfma_f32_32x32x16_bf16 v[0:15], v[102:105], v[118:121], v[0:15]
	ds_read_b64_tr_b16 v[118:119], v152 offset:0x1200
	ds_read_b64_tr_b16 v[120:121], v152 offset:0x1a00
	v_mfma_f32_32x32x16_bf16 v[0:15], v[106:109], v[122:125], v[0:15]
	ds_read_b64_tr_b16 v[122:123], v152 offset:0x2200
	ds_read_b64_tr_b16 v[124:125], v152 offset:0x2a00
	v_mfma_f32_32x32x16_bf16 v[0:15], v[110:113], v[126:129], v[0:15]
	ds_read_b64_tr_b16 v[126:127], v152 offset:0x3200
	ds_read_b64_tr_b16 v[128:129], v152 offset:0x3a00
	s_waitcnt lgkmcnt(0)
	v_mfma_f32_32x32x16_bf16 v[48:63], v[98:101], v[114:117], v[48:63]
	ds_read_b64_tr_b16 v[114:115], v152 offset:0x400
	ds_read_b64_tr_b16 v[116:117], v152 offset:0xc00
	v_mfma_f32_32x32x16_bf16 v[48:63], v[102:105], v[118:121], v[48:63]
	ds_read_b64_tr_b16 v[118:119], v152 offset:0x1400
	ds_read_b64_tr_b16 v[120:121], v152 offset:0x1c00
	v_mfma_f32_32x32x16_bf16 v[48:63], v[106:109], v[122:125], v[48:63]
	ds_read_b64_tr_b16 v[122:123], v152 offset:0x2400
	ds_read_b64_tr_b16 v[124:125], v152 offset:0x2c00
	v_mfma_f32_32x32x16_bf16 v[48:63], v[110:113], v[126:129], v[48:63]
	ds_read_b64_tr_b16 v[126:127], v152 offset:0x3400
	ds_read_b64_tr_b16 v[128:129], v152 offset:0x3c00
	s_waitcnt lgkmcnt(0)
	v_mfma_f32_32x32x16_bf16 v[32:47], v[98:101], v[114:117], v[32:47]
	ds_read_b64_tr_b16 v[114:115], v152 offset:0x600
	ds_read_b64_tr_b16 v[116:117], v152 offset:0xe00
	v_mfma_f32_32x32x16_bf16 v[32:47], v[102:105], v[118:121], v[32:47]
	ds_read_b64_tr_b16 v[118:119], v152 offset:0x1600
	ds_read_b64_tr_b16 v[120:121], v152 offset:0x1e00
	v_mfma_f32_32x32x16_bf16 v[32:47], v[106:109], v[122:125], v[32:47]
	ds_read_b64_tr_b16 v[122:123], v152 offset:0x2600
	ds_read_b64_tr_b16 v[124:125], v152 offset:0x2e00
	v_mfma_f32_32x32x16_bf16 v[32:47], v[110:113], v[126:129], v[32:47]
	ds_read_b64_tr_b16 v[126:127], v152 offset:0x3600
	ds_read_b64_tr_b16 v[128:129], v152 offset:0x3e00
	s_waitcnt lgkmcnt(0)
	v_mfma_f32_32x32x16_bf16 v[16:31], v[98:101], v[114:117], v[16:31]
	v_max_f32_e32 v98, v81, v81
	v_max_f32_e32 v99, v80, v80
	v_max_f32_e32 v98, v99, v98
	v_max3_f32 v98, v98, v82, v83
	v_max3_f32 v98, v98, v84, v85
	v_max3_f32 v98, v98, v86, v87
	v_max3_f32 v98, v98, v88, v89
	v_max3_f32 v98, v98, v90, v91
	v_max3_f32 v98, v98, v92, v93
	v_mfma_f32_32x32x16_bf16 v[16:31], v[102:105], v[118:121], v[16:31]
	v_max3_f32 v98, v98, v94, v95
	v_max3_f32 v98, v98, v64, v65
	v_max3_f32 v98, v98, v66, v67
	v_max3_f32 v98, v98, v68, v69
	v_max3_f32 v98, v98, v70, v71
	v_max3_f32 v98, v98, v72, v73
	v_max3_f32 v98, v98, v74, v75
	v_max3_f32 v98, v98, v76, v77
	v_mfma_f32_32x32x16_bf16 v[16:31], v[106:109], v[122:125], v[16:31]
	v_max3_f32 v98, v98, v78, v79
	v_mov_b32_e32 v99, v98
	s_nop 1
	v_permlane32_swap_b32_e32 v98, v99
	v_max_f32_e32 v99, v99, v99
	v_max_f32_e32 v98, v98, v98
	v_max_f32_e32 v98, v98, v99
	v_sub_f32_e32 v99, v98, v188
	v_cmp_ge_f32_e32 vcc, s1, v99
	v_max_f32_e32 v99, v188, v188
	v_max_f32_e32 v99, v99, v98
	v_mfma_f32_32x32x16_bf16 v[16:31], v[110:113], v[126:129], v[16:31]
	v_sub_f32_e32 v98, v188, v99
	v_mul_f32_e32 v98, 0x3dd53b94, v98
	v_exp_f32_e32 v98, v98
	s_cmp_eq_u64 vcc, exec
	s_cselect_b64 s[6:7], -1, 0
	v_cndmask_b32_e64 v98, v98, 1.0, s[6:7]
	v_cmp_gt_f32_e32 vcc, 1.0, v98
	s_barrier
	s_cbranch_vccz .LBB0_2205
	s_and_saveexec_b64 s[10:11], s[4:5]
	ds_write_b32 v174, v98 offset:128
	s_or_b64 exec, exec, s[10:11]
	s_waitcnt lgkmcnt(0)
	v_add_u32_e32 v112, v137, v160
	ds_read_b128 v[100:103], v112 offset:224
	ds_read_b128 v[104:107], v112 offset:192
	ds_read_b128 v[108:111], v112 offset:160
	ds_read_b128 v[112:115], v112 offset:128
	s_waitcnt lgkmcnt(3)
	v_pk_mul_f32 v[12:13], v[12:13], v[100:101]
	s_waitcnt lgkmcnt(2)
	v_pk_mul_f32 v[8:9], v[8:9], v[104:105]
	s_waitcnt lgkmcnt(1)
	v_pk_mul_f32 v[4:5], v[4:5], v[108:109]
	v_pk_mul_f32 v[14:15], v[14:15], v[102:103]
	v_pk_mul_f32 v[10:11], v[10:11], v[106:107]
	v_pk_mul_f32 v[6:7], v[6:7], v[110:111]
	s_waitcnt lgkmcnt(0)
	v_pk_mul_f32 v[2:3], v[2:3], v[114:115]
	v_pk_mul_f32 v[0:1], v[0:1], v[112:113]
	v_pk_mul_f32 v[60:61], v[60:61], v[100:101]
	v_pk_mul_f32 v[56:57], v[56:57], v[104:105]
	v_pk_mul_f32 v[52:53], v[52:53], v[108:109]
	v_pk_mul_f32 v[62:63], v[62:63], v[102:103]
	v_pk_mul_f32 v[58:59], v[58:59], v[106:107]
	v_pk_mul_f32 v[54:55], v[54:55], v[110:111]
	v_pk_mul_f32 v[50:51], v[50:51], v[114:115]
	v_pk_mul_f32 v[48:49], v[48:49], v[112:113]
	v_pk_mul_f32 v[44:45], v[44:45], v[100:101]
	v_pk_mul_f32 v[40:41], v[40:41], v[104:105]
	v_pk_mul_f32 v[36:37], v[36:37], v[108:109]
	v_pk_mul_f32 v[46:47], v[46:47], v[102:103]
	v_pk_mul_f32 v[42:43], v[42:43], v[106:107]
	v_pk_mul_f32 v[38:39], v[38:39], v[110:111]
	v_pk_mul_f32 v[34:35], v[34:35], v[114:115]
	v_pk_mul_f32 v[32:33], v[32:33], v[112:113]
	v_pk_mul_f32 v[28:29], v[28:29], v[100:101]
	v_pk_mul_f32 v[24:25], v[24:25], v[104:105]
	v_pk_mul_f32 v[20:21], v[20:21], v[108:109]
	v_pk_mul_f32 v[30:31], v[30:31], v[102:103]
	v_pk_mul_f32 v[26:27], v[26:27], v[106:107]
	v_pk_mul_f32 v[22:23], v[22:23], v[110:111]
	v_pk_mul_f32 v[18:19], v[18:19], v[114:115]
	v_pk_mul_f32 v[16:17], v[16:17], v[112:113]
